# gdn-out phase: 16 of 20 per-row butterfly steps as DPP adds instead of ds_bpermute; on top of prep D1/pk/DPP
# baseline (speedup 1.0000x reference)
; __device__ __forceinline__ unsigned pk2(float lo, float hi) { return __builtin_bit_cast(unsigned, __builtin_convertvector((f32x2p){lo, hi}, bf16x2p)); }
; __device__ __forceinline__ float shx(float v, int m, int lane) { return __builtin_bit_cast(float, __builtin_amdgcn_ds_bpermute((lane ^ m) << 2, __builtin_bit_cast(int, v))); }
; __device__ __forceinline__ float siluf(float v) { return v / (1.f + __expf(-v)); }
; __device__ __forceinline__ void gdn_out_phase(const Frame& F0, const Args& a0, int l, bool last) {
;     ...
;     for (int m = gw; m < M; m += NGW) {
;         if (last && (m % TT) < CTXL) continue;
;         v2u oa[4], ob[4], gz[4];
; #pragma unroll
;         for (int k = 0; k < 4; ++k) { const int ch = (F.lane + 64 * k) * 4;
;             oa[k] = *(const v2u*)(GO + (size_t)m * 1024 + ch); ob[k] = *(const v2u*)(GO + (size_t)M * 1024 + (size_t)m * 1024 + ch); gz[k] = *(const v2u*)(Z + (size_t)m * ZP + OFF_GATE + ch); }
;         __builtin_amdgcn_sched_barrier(0);
; #pragma unroll
;         for (int k = 0; k < 4; ++k) { const int ch = (F.lane + 64 * k) * 4;
;             const f32x4 o = (f32x4){bflo(oa[k].x) + bflo(ob[k].x), bfhi(oa[k].x) + bfhi(ob[k].x), bflo(oa[k].y) + bflo(ob[k].y), bfhi(oa[k].y) + bfhi(ob[k].y)};
;             float ss = (o.x * o.x + o.y * o.y) + (o.z * o.z + o.w * o.w);
; #pragma unroll
;             for (int q = 1; q < 32; q <<= 1) ss += shx(ss, q, F.lane);
;             const float rn = 1.0f / sqrtf(ss * (1.f / 128.f) + EPS);
;             const float g0 = bflo(gz[k].x), g1 = bfhi(gz[k].x), g2 = bflo(gz[k].y), g3 = bfhi(gz[k].y);
;             v2u w; w.x = pk2(o.x * rn * gn[k].x * siluf(g0), o.y * rn * gn[k].y * siluf(g1));
;             w.y = pk2(o.z * rn * gn[k].z * siluf(g2), o.w * rn * gn[k].w * siluf(g3));
;             *(v2u*)(MIX + (size_t)m * 2048 + 1024 + ch) = w; }
.LBB0_742:
	s_mul_hi_i32 s2, s6, 0x38e38e39
	s_lshr_b32 s3, s2, 31
	s_ashr_i32 s2, s2, 9
	s_add_i32 s2, s2, s3
	s_mulk_i32 s2, 0x900
	s_sub_i32 s2, s6, s2
	s_cmpk_lt_i32 s2, 0x100
	s_cselect_b64 s[2:3], -1, 0
	s_and_b64 s[2:3], s[76:77], s[2:3]
	s_and_b64 vcc, exec, s[2:3]
	s_cbranch_vccnz .LBB0_741
	v_lshl_add_u64 v[22:23], s[4:5], 0, v[20:21]
	v_add_co_u32_e32 v24, vcc, 0x4b800000, v22
	v_lshl_add_u64 v[28:29], s[4:5], 0, v[18:19]
	s_nop 0
	v_addc_co_u32_e32 v25, vcc, 0, v23, vcc
	v_add_co_u32_e32 v22, vcc, 0x4ca00000, v22
	v_lshl_add_u64 v[34:35], s[4:5], 0, v[16:17]
	s_nop 0
	v_addc_co_u32_e32 v23, vcc, 0, v23, vcc
	global_load_dwordx2 v[42:43], v[24:25], off
	global_load_dwordx2 v[36:37], v[24:25], off offset:512
	global_load_dwordx2 v[30:31], v[24:25], off offset:1024
	s_nop 0
	global_load_dwordx2 v[24:25], v[24:25], off offset:1536
	s_nop 0
	global_load_dwordx2 v[50:51], v[22:23], off
	global_load_dwordx2 v[38:39], v[22:23], off offset:512
	global_load_dwordx2 v[32:33], v[22:23], off offset:1024
	global_load_dwordx2 v[26:27], v[22:23], off offset:1536
	v_lshl_add_u64 v[22:23], s[4:5], 0, v[12:13]
	v_lshl_add_u64 v[40:41], s[4:5], 0, v[14:15]
	global_load_dwordx2 v[52:53], v[28:29], off
	s_nop 0
	global_load_dwordx2 v[34:35], v[34:35], off
	s_nop 0
	global_load_dwordx2 v[28:29], v[40:41], off
	s_nop 0
	global_load_dwordx2 v[22:23], v[22:23], off
	s_waitcnt vmcnt(11)
	v_lshlrev_b32_e32 v40, 16, v43
	v_and_b32_e32 v41, 0xffff0000, v43
	s_waitcnt vmcnt(7)
	v_lshlrev_b32_e32 v54, 16, v51
	v_and_b32_e32 v55, 0xffff0000, v51
	v_pk_add_f32 v[40:41], v[40:41], v[54:55]
	v_lshlrev_b32_e32 v54, 16, v42
	v_and_b32_e32 v55, 0xffff0000, v42
	v_lshlrev_b32_e32 v42, 16, v50
	v_and_b32_e32 v43, 0xffff0000, v50
	v_pk_add_f32 v[42:43], v[54:55], v[42:43]
	v_mov_b32_e32 v55, v41
	v_mov_b32_e32 v54, v43
	v_mov_b32_e32 v50, v42
	v_mov_b32_e32 v51, v40
	v_pk_mul_f32 v[54:55], v[54:55], v[54:55]
	s_waitcnt vmcnt(3)
	v_lshlrev_b32_e32 v49, 16, v53
	v_pk_fma_f32 v[50:51], v[50:51], v[50:51], v[54:55]
	v_lshlrev_b32_e32 v54, 16, v52
	v_add_f32_e32 v50, v50, v51
	v_and_b32_e32 v55, 0xffff0000, v52
	v_and_b32_e32 v56, 0xffff0000, v53
	v_mul_f32_e32 v52, 0xbfb8aa3b, v54
	v_mul_f32_e32 v53, 0xbfb8aa3b, v55
	v_exp_f32_e32 v52, v52
	v_exp_f32_e32 v53, v53
	v_add_f32_dpp v50, v50, v50 quad_perm:[1,0,3,2] row_mask:0xf bank_mask:0xf
	v_pk_add_f32 v[52:53], v[52:53], 1.0 op_sel_hi:[1,0]
	s_nop 0
	v_div_scale_f32 v57, s[2:3], v53, v53, v55
	v_rcp_f32_e32 v58, v57
	v_add_f32_dpp v50, v50, v50 quad_perm:[2,3,0,1] row_mask:0xf bank_mask:0xf
	v_fma_f32 v59, -v57, v58, 1.0
	v_fmac_f32_e32 v58, v59, v58
	v_div_scale_f32 v59, vcc, v55, v53, v55
	v_mul_f32_e32 v60, v59, v58
	v_fma_f32 v61, -v57, v60, v59
	v_fmac_f32_e32 v60, v61, v58
	v_add_f32_dpp v50, v50, v50 row_half_mirror row_mask:0xf bank_mask:0xf
	v_fma_f32 v57, -v57, v60, v59
	v_div_fmas_f32 v57, v57, v58, v60
	v_div_fixup_f32 v53, v57, v53, v55
	v_div_scale_f32 v55, s[2:3], v52, v52, v54
	v_rcp_f32_e32 v57, v55
	v_add_f32_dpp v50, v50, v50 row_mirror row_mask:0xf bank_mask:0xf
	ds_bpermute_b32 v51, v48, v50
	v_fma_f32 v58, -v55, v57, 1.0
	v_fmac_f32_e32 v57, v58, v57
	v_div_scale_f32 v58, vcc, v54, v52, v54
	v_mul_f32_e32 v59, v58, v57
	v_fma_f32 v60, -v55, v59, v58
	v_fmac_f32_e32 v59, v60, v57
	s_waitcnt lgkmcnt(0)
	v_add_f32_e32 v50, v50, v51
	v_fma_f32 v55, -v55, v59, v58
	v_fmamk_f32 v50, v50, 0x3c000000, v182
	v_div_fmas_f32 v55, v55, v57, v59
	v_cmp_gt_f32_e32 vcc, s74, v50
	v_mul_f32_e32 v51, 0x4f800000, v50
	v_div_fixup_f32 v52, v55, v52, v54
	v_cndmask_b32_e32 v50, v50, v51, vcc
	v_sqrt_f32_e32 v51, v50
	s_nop 0
	v_add_u32_e32 v54, -1, v51
	v_fma_f32 v55, -v54, v51, v50
	v_cmp_ge_f32_e64 s[2:3], 0, v55
	v_add_u32_e32 v55, 1, v51
	s_nop 0
	v_cndmask_b32_e64 v54, v51, v54, s[2:3]
	v_fma_f32 v51, -v55, v51, v50
	v_cmp_lt_f32_e64 s[2:3], 0, v51
	s_nop 1
	v_cndmask_b32_e64 v51, v54, v55, s[2:3]
	v_mul_f32_e32 v54, 0x37800000, v51
	v_cndmask_b32_e32 v51, v51, v54, vcc
	v_cmp_class_f32_e32 vcc, v50, v183
	s_nop 1
	v_cndmask_b32_e32 v50, v51, v50, vcc
	v_div_scale_f32 v51, s[2:3], v50, v50, 1.0
	v_rcp_f32_e32 v54, v51
	s_nop 0
	v_fma_f32 v55, -v51, v54, 1.0
	v_fmac_f32_e32 v54, v55, v54
	v_div_scale_f32 v55, vcc, 1.0, v50, 1.0
	v_mul_f32_e32 v57, v55, v54
	v_fma_f32 v58, -v51, v57, v55
	v_fmac_f32_e32 v57, v58, v54
	v_fma_f32 v51, -v51, v57, v55
	v_div_fmas_f32 v51, v51, v54, v57
	v_div_fixup_f32 v50, v51, v50, 1.0
	v_pk_mul_f32 v[42:43], v[42:43], v[50:51] op_sel_hi:[1,0]
	v_pk_mul_f32 v[40:41], v[40:41], v[50:51] op_sel_hi:[1,0]
	v_pk_mul_f32 v[42:43], v[0:1], v[42:43]
	v_pk_mul_f32 v[40:41], v[2:3], v[40:41]
	v_pk_mul_f32 v[42:43], v[52:53], v[42:43]
	s_nop 0
	v_cvt_pk_bf16_f32 v42, v42, v43
	v_mul_f32_e32 v43, 0xbfb8aa3b, v49
	v_exp_f32_e32 v52, v43
	v_mul_f32_e32 v43, 0xbfb8aa3b, v56
	v_exp_f32_e32 v53, v43
	s_nop 0
	v_pk_add_f32 v[50:51], v[52:53], 1.0 op_sel_hi:[1,0]
	s_nop 0
	v_div_scale_f32 v43, s[2:3], v51, v51, v56
	v_rcp_f32_e32 v52, v43
	s_nop 0
	v_fma_f32 v53, -v43, v52, 1.0
	v_fmac_f32_e32 v52, v53, v52
	v_div_scale_f32 v53, vcc, v56, v51, v56
	v_mul_f32_e32 v54, v53, v52
	v_fma_f32 v55, -v43, v54, v53
	v_fmac_f32_e32 v54, v55, v52
	v_fma_f32 v43, -v43, v54, v53
	v_div_fmas_f32 v43, v43, v52, v54
	v_div_fixup_f32 v51, v43, v51, v56
	v_div_scale_f32 v43, s[2:3], v50, v50, v49
	v_rcp_f32_e32 v52, v43
	s_nop 0
	v_fma_f32 v53, -v43, v52, 1.0
	v_fmac_f32_e32 v52, v53, v52
	v_div_scale_f32 v53, vcc, v49, v50, v49
	v_mul_f32_e32 v54, v53, v52
	v_fma_f32 v55, -v43, v54, v53
	v_fmac_f32_e32 v54, v55, v52
	v_fma_f32 v43, -v43, v54, v53
	v_div_fmas_f32 v43, v43, v52, v54
	v_div_fixup_f32 v50, v43, v50, v49
	v_pk_mul_f32 v[40:41], v[50:51], v[40:41]
	s_waitcnt vmcnt(2)
; __device__ __forceinline__ unsigned pk2(float lo, float hi) { return __builtin_bit_cast(unsigned, __builtin_convertvector((f32x2p){lo, hi}, bf16x2p)); }
; __device__ __forceinline__ float shx(float v, int m, int lane) { return __builtin_bit_cast(float, __builtin_amdgcn_ds_bpermute((lane ^ m) << 2, __builtin_bit_cast(int, v))); }
; __device__ __forceinline__ float siluf(float v) { return v / (1.f + __expf(-v)); }
; __device__ __forceinline__ void gdn_out_phase(const Frame& F0, const Args& a0, int l, bool last) {
;     ...
;     for (int m = gw; m < M; m += NGW) {
;         if (last && (m % TT) < CTXL) continue;
;         v2u oa[4], ob[4], gz[4];
; #pragma unroll
;         for (int k = 0; k < 4; ++k) { const int ch = (F.lane + 64 * k) * 4;
;             oa[k] = *(const v2u*)(GO + (size_t)m * 1024 + ch); ob[k] = *(const v2u*)(GO + (size_t)M * 1024 + (size_t)m * 1024 + ch); gz[k] = *(const v2u*)(Z + (size_t)m * ZP + OFF_GATE + ch); }
;         __builtin_amdgcn_sched_barrier(0);
; #pragma unroll
;         for (int k = 0; k < 4; ++k) { const int ch = (F.lane + 64 * k) * 4;
;             const f32x4 o = (f32x4){bflo(oa[k].x) + bflo(ob[k].x), bfhi(oa[k].x) + bfhi(ob[k].x), bflo(oa[k].y) + bflo(ob[k].y), bfhi(oa[k].y) + bfhi(ob[k].y)};
;             float ss = (o.x * o.x + o.y * o.y) + (o.z * o.z + o.w * o.w);
; #pragma unroll
;             for (int q = 1; q < 32; q <<= 1) ss += shx(ss, q, F.lane);
;             const float rn = 1.0f / sqrtf(ss * (1.f / 128.f) + EPS);
;             const float g0 = bflo(gz[k].x), g1 = bfhi(gz[k].x), g2 = bflo(gz[k].y), g3 = bfhi(gz[k].y);
;             v2u w; w.x = pk2(o.x * rn * gn[k].x * siluf(g0), o.y * rn * gn[k].y * siluf(g1));
;             w.y = pk2(o.z * rn * gn[k].z * siluf(g2), o.w * rn * gn[k].w * siluf(g3));
;             *(v2u*)(MIX + (size_t)m * 2048 + 1024 + ch) = w; }
	v_lshlrev_b32_e32 v49, 16, v35
	v_cvt_pk_bf16_f32 v43, v40, v41
	v_lshl_add_u64 v[40:41], s[4:5], 0, v[10:11]
	global_store_dwordx2 v[40:41], v[42:43], off
	v_lshlrev_b32_e32 v40, 16, v37
	v_and_b32_e32 v41, 0xffff0000, v37
	v_lshlrev_b32_e32 v42, 16, v39
	v_and_b32_e32 v43, 0xffff0000, v39
	v_pk_add_f32 v[40:41], v[40:41], v[42:43]
	v_lshlrev_b32_e32 v42, 16, v36
	v_and_b32_e32 v43, 0xffff0000, v36
	v_lshlrev_b32_e32 v36, 16, v38
	v_and_b32_e32 v37, 0xffff0000, v38
	v_pk_add_f32 v[36:37], v[42:43], v[36:37]
	v_mov_b32_e32 v43, v41
	v_mov_b32_e32 v42, v37
	v_mov_b32_e32 v38, v36
	v_mov_b32_e32 v39, v40
	v_pk_mul_f32 v[42:43], v[42:43], v[42:43]
	v_and_b32_e32 v50, 0xffff0000, v35
	v_pk_fma_f32 v[38:39], v[38:39], v[38:39], v[42:43]
	v_lshlrev_b32_e32 v42, 16, v34
	v_add_f32_e32 v38, v38, v39
	v_and_b32_e32 v43, 0xffff0000, v34
	v_mul_f32_e32 v34, 0xbfb8aa3b, v42
	v_mul_f32_e32 v35, 0xbfb8aa3b, v43
	v_exp_f32_e32 v34, v34
	v_exp_f32_e32 v35, v35
	v_add_f32_dpp v38, v38, v38 quad_perm:[1,0,3,2] row_mask:0xf bank_mask:0xf
	v_pk_add_f32 v[34:35], v[34:35], 1.0 op_sel_hi:[1,0]
	s_nop 0
	v_div_scale_f32 v51, s[2:3], v35, v35, v43
	v_rcp_f32_e32 v52, v51
	v_add_f32_dpp v38, v38, v38 quad_perm:[2,3,0,1] row_mask:0xf bank_mask:0xf
	v_fma_f32 v53, -v51, v52, 1.0
	v_fmac_f32_e32 v52, v53, v52
	v_div_scale_f32 v53, vcc, v43, v35, v43
	v_mul_f32_e32 v54, v53, v52
	v_fma_f32 v55, -v51, v54, v53
	v_fmac_f32_e32 v54, v55, v52
	v_add_f32_dpp v38, v38, v38 row_half_mirror row_mask:0xf bank_mask:0xf
	v_fma_f32 v51, -v51, v54, v53
	v_div_fmas_f32 v51, v51, v52, v54
	v_div_fixup_f32 v35, v51, v35, v43
	v_div_scale_f32 v43, s[2:3], v34, v34, v42
	v_rcp_f32_e32 v51, v43
	v_add_f32_dpp v38, v38, v38 row_mirror row_mask:0xf bank_mask:0xf
	ds_bpermute_b32 v39, v48, v38
	v_fma_f32 v52, -v43, v51, 1.0
	v_fmac_f32_e32 v51, v52, v51
	v_div_scale_f32 v52, vcc, v42, v34, v42
	v_mul_f32_e32 v53, v52, v51
	v_fma_f32 v54, -v43, v53, v52
	v_fmac_f32_e32 v53, v54, v51
	s_waitcnt lgkmcnt(0)
	v_add_f32_e32 v38, v38, v39
	v_fma_f32 v43, -v43, v53, v52
	v_fmamk_f32 v38, v38, 0x3c000000, v182
	v_div_fmas_f32 v43, v43, v51, v53
	v_cmp_gt_f32_e32 vcc, s74, v38
	v_mul_f32_e32 v39, 0x4f800000, v38
	v_div_fixup_f32 v34, v43, v34, v42
	v_cndmask_b32_e32 v38, v38, v39, vcc
	v_sqrt_f32_e32 v39, v38
	s_nop 0
	v_add_u32_e32 v42, -1, v39
	v_fma_f32 v43, -v42, v39, v38
	v_cmp_ge_f32_e64 s[2:3], 0, v43
	v_add_u32_e32 v43, 1, v39
	s_nop 0
	v_cndmask_b32_e64 v42, v39, v42, s[2:3]
	v_fma_f32 v39, -v43, v39, v38
	v_cmp_lt_f32_e64 s[2:3], 0, v39
	s_nop 1
	v_cndmask_b32_e64 v39, v42, v43, s[2:3]
	v_mul_f32_e32 v42, 0x37800000, v39
	v_cndmask_b32_e32 v39, v39, v42, vcc
	v_cmp_class_f32_e32 vcc, v38, v183
	s_nop 1
	v_cndmask_b32_e32 v38, v39, v38, vcc
	v_div_scale_f32 v39, s[2:3], v38, v38, 1.0
	v_rcp_f32_e32 v42, v39
	s_nop 0
	v_fma_f32 v43, -v39, v42, 1.0
	v_fmac_f32_e32 v42, v43, v42
	v_div_scale_f32 v43, vcc, 1.0, v38, 1.0
	v_mul_f32_e32 v51, v43, v42
	v_fma_f32 v52, -v39, v51, v43
	v_fmac_f32_e32 v51, v52, v42
	v_fma_f32 v39, -v39, v51, v43
	v_div_fmas_f32 v39, v39, v42, v51
	v_div_fixup_f32 v38, v39, v38, 1.0
	v_pk_mul_f32 v[36:37], v[36:37], v[38:39] op_sel_hi:[1,0]
	v_pk_mul_f32 v[38:39], v[40:41], v[38:39] op_sel_hi:[1,0]
	v_pk_mul_f32 v[36:37], v[0:1], v[36:37]
	v_pk_mul_f32 v[38:39], v[2:3], v[38:39]
	v_pk_mul_f32 v[34:35], v[34:35], v[36:37]
	s_nop 0
	v_cvt_pk_bf16_f32 v34, v34, v35
	v_mul_f32_e32 v35, 0xbfb8aa3b, v49
	v_exp_f32_e32 v36, v35
	v_mul_f32_e32 v35, 0xbfb8aa3b, v50
	v_exp_f32_e32 v37, v35
	s_nop 0
	v_pk_add_f32 v[36:37], v[36:37], 1.0 op_sel_hi:[1,0]
	s_nop 0
	v_div_scale_f32 v35, s[2:3], v37, v37, v50
	v_rcp_f32_e32 v40, v35
	s_nop 0
	v_fma_f32 v41, -v35, v40, 1.0
	v_fmac_f32_e32 v40, v41, v40
	v_div_scale_f32 v41, vcc, v50, v37, v50
	v_mul_f32_e32 v42, v41, v40
	v_fma_f32 v43, -v35, v42, v41
	v_fmac_f32_e32 v42, v43, v40
	v_fma_f32 v35, -v35, v42, v41
	v_div_fmas_f32 v35, v35, v40, v42
	v_div_fixup_f32 v37, v35, v37, v50
	v_div_scale_f32 v35, s[2:3], v36, v36, v49
	v_rcp_f32_e32 v40, v35
	s_nop 0
	v_fma_f32 v41, -v35, v40, 1.0
	v_fmac_f32_e32 v40, v41, v40
	v_div_scale_f32 v41, vcc, v49, v36, v49
	v_mul_f32_e32 v42, v41, v40
	v_fma_f32 v43, -v35, v42, v41
	v_fmac_f32_e32 v42, v43, v40
	v_fma_f32 v35, -v35, v42, v41
	v_div_fmas_f32 v35, v35, v40, v42
	v_div_fixup_f32 v36, v35, v36, v49
	v_pk_mul_f32 v[36:37], v[36:37], v[38:39]
	s_waitcnt vmcnt(2)
	v_lshlrev_b32_e32 v38, 16, v29
	v_cvt_pk_bf16_f32 v35, v36, v37
	v_lshl_add_u64 v[36:37], s[4:5], 0, v[8:9]
	global_store_dwordx2 v[36:37], v[34:35], off
	v_lshlrev_b32_e32 v34, 16, v31
	v_and_b32_e32 v35, 0xffff0000, v31
	v_lshlrev_b32_e32 v36, 16, v33
	v_and_b32_e32 v37, 0xffff0000, v33
	v_pk_add_f32 v[34:35], v[34:35], v[36:37]
	v_lshlrev_b32_e32 v36, 16, v30
	v_and_b32_e32 v37, 0xffff0000, v30
	v_lshlrev_b32_e32 v30, 16, v32
	v_and_b32_e32 v31, 0xffff0000, v32
	v_pk_add_f32 v[30:31], v[36:37], v[30:31]
	v_mov_b32_e32 v37, v35
	v_mov_b32_e32 v36, v31
	v_mov_b32_e32 v32, v30
	v_mov_b32_e32 v33, v34
	v_pk_mul_f32 v[36:37], v[36:37], v[36:37]
	v_and_b32_e32 v39, 0xffff0000, v29
	v_pk_fma_f32 v[32:33], v[32:33], v[32:33], v[36:37]
	v_lshlrev_b32_e32 v36, 16, v28
	v_add_f32_e32 v32, v32, v33
	v_and_b32_e32 v37, 0xffff0000, v28
	v_mul_f32_e32 v28, 0xbfb8aa3b, v36
	v_mul_f32_e32 v29, 0xbfb8aa3b, v37
	v_exp_f32_e32 v28, v28
	v_exp_f32_e32 v29, v29
	v_add_f32_dpp v32, v32, v32 quad_perm:[1,0,3,2] row_mask:0xf bank_mask:0xf
	v_pk_add_f32 v[28:29], v[28:29], 1.0 op_sel_hi:[1,0]
	s_nop 0
	v_div_scale_f32 v40, s[2:3], v29, v29, v37
	v_rcp_f32_e32 v41, v40
	v_add_f32_dpp v32, v32, v32 quad_perm:[2,3,0,1] row_mask:0xf bank_mask:0xf
	v_fma_f32 v42, -v40, v41, 1.0
	v_fmac_f32_e32 v41, v42, v41
	v_div_scale_f32 v42, vcc, v37, v29, v37
	v_mul_f32_e32 v43, v42, v41
	v_fma_f32 v49, -v40, v43, v42
	v_fmac_f32_e32 v43, v49, v41
	v_add_f32_dpp v32, v32, v32 row_half_mirror row_mask:0xf bank_mask:0xf
	v_fma_f32 v40, -v40, v43, v42
	v_div_fmas_f32 v40, v40, v41, v43
	v_div_fixup_f32 v29, v40, v29, v37
	v_div_scale_f32 v37, s[2:3], v28, v28, v36
	v_rcp_f32_e32 v40, v37
	v_add_f32_dpp v32, v32, v32 row_mirror row_mask:0xf bank_mask:0xf
	ds_bpermute_b32 v33, v48, v32
	v_fma_f32 v41, -v37, v40, 1.0
	v_fmac_f32_e32 v40, v41, v40
	v_div_scale_f32 v41, vcc, v36, v28, v36
	v_mul_f32_e32 v42, v41, v40
	v_fma_f32 v43, -v37, v42, v41
	v_fmac_f32_e32 v42, v43, v40
	s_waitcnt lgkmcnt(0)
; __device__ __forceinline__ unsigned pk2(float lo, float hi) { return __builtin_bit_cast(unsigned, __builtin_convertvector((f32x2p){lo, hi}, bf16x2p)); }
; __device__ __forceinline__ float shx(float v, int m, int lane) { return __builtin_bit_cast(float, __builtin_amdgcn_ds_bpermute((lane ^ m) << 2, __builtin_bit_cast(int, v))); }
; __device__ __forceinline__ float siluf(float v) { return v / (1.f + __expf(-v)); }
; __device__ __forceinline__ void gdn_out_phase(const Frame& F0, const Args& a0, int l, bool last) {
;     ...
;     for (int m = gw; m < M; m += NGW) {
;         if (last && (m % TT) < CTXL) continue;
;         v2u oa[4], ob[4], gz[4];
; #pragma unroll
;         for (int k = 0; k < 4; ++k) { const int ch = (F.lane + 64 * k) * 4;
;             oa[k] = *(const v2u*)(GO + (size_t)m * 1024 + ch); ob[k] = *(const v2u*)(GO + (size_t)M * 1024 + (size_t)m * 1024 + ch); gz[k] = *(const v2u*)(Z + (size_t)m * ZP + OFF_GATE + ch); }
;         __builtin_amdgcn_sched_barrier(0);
; #pragma unroll
;         for (int k = 0; k < 4; ++k) { const int ch = (F.lane + 64 * k) * 4;
;             const f32x4 o = (f32x4){bflo(oa[k].x) + bflo(ob[k].x), bfhi(oa[k].x) + bfhi(ob[k].x), bflo(oa[k].y) + bflo(ob[k].y), bfhi(oa[k].y) + bfhi(ob[k].y)};
;             float ss = (o.x * o.x + o.y * o.y) + (o.z * o.z + o.w * o.w);
; #pragma unroll
;             for (int q = 1; q < 32; q <<= 1) ss += shx(ss, q, F.lane);
;             const float rn = 1.0f / sqrtf(ss * (1.f / 128.f) + EPS);
;             const float g0 = bflo(gz[k].x), g1 = bfhi(gz[k].x), g2 = bflo(gz[k].y), g3 = bfhi(gz[k].y);
;             v2u w; w.x = pk2(o.x * rn * gn[k].x * siluf(g0), o.y * rn * gn[k].y * siluf(g1));
;             w.y = pk2(o.z * rn * gn[k].z * siluf(g2), o.w * rn * gn[k].w * siluf(g3));
;             *(v2u*)(MIX + (size_t)m * 2048 + 1024 + ch) = w; }
	v_add_f32_e32 v32, v32, v33
	v_fma_f32 v37, -v37, v42, v41
	v_fmamk_f32 v32, v32, 0x3c000000, v182
	v_div_fmas_f32 v37, v37, v40, v42
	v_cmp_gt_f32_e32 vcc, s74, v32
	v_mul_f32_e32 v33, 0x4f800000, v32
	v_div_fixup_f32 v28, v37, v28, v36
	v_cndmask_b32_e32 v32, v32, v33, vcc
	v_sqrt_f32_e32 v33, v32
	s_nop 0
	v_add_u32_e32 v36, -1, v33
	v_fma_f32 v37, -v36, v33, v32
	v_cmp_ge_f32_e64 s[2:3], 0, v37
	v_add_u32_e32 v37, 1, v33
	s_nop 0
	v_cndmask_b32_e64 v36, v33, v36, s[2:3]
	v_fma_f32 v33, -v37, v33, v32
	v_cmp_lt_f32_e64 s[2:3], 0, v33
	s_nop 1
	v_cndmask_b32_e64 v33, v36, v37, s[2:3]
	v_mul_f32_e32 v36, 0x37800000, v33
	v_cndmask_b32_e32 v33, v33, v36, vcc
	v_cmp_class_f32_e32 vcc, v32, v183
	s_nop 1
	v_cndmask_b32_e32 v32, v33, v32, vcc
	v_div_scale_f32 v33, s[2:3], v32, v32, 1.0
	v_rcp_f32_e32 v36, v33
	s_nop 0
	v_fma_f32 v37, -v33, v36, 1.0
	v_fmac_f32_e32 v36, v37, v36
	v_div_scale_f32 v37, vcc, 1.0, v32, 1.0
	v_mul_f32_e32 v40, v37, v36
	v_fma_f32 v41, -v33, v40, v37
	v_fmac_f32_e32 v40, v41, v36
	v_fma_f32 v33, -v33, v40, v37
	v_div_fmas_f32 v33, v33, v36, v40
	v_div_fixup_f32 v32, v33, v32, 1.0
	v_pk_mul_f32 v[30:31], v[30:31], v[32:33] op_sel_hi:[1,0]
	v_pk_mul_f32 v[32:33], v[34:35], v[32:33] op_sel_hi:[1,0]
	v_pk_mul_f32 v[30:31], v[0:1], v[30:31]
	v_pk_mul_f32 v[32:33], v[2:3], v[32:33]
	v_pk_mul_f32 v[28:29], v[28:29], v[30:31]
	s_nop 0
	v_cvt_pk_bf16_f32 v28, v28, v29
	v_mul_f32_e32 v29, 0xbfb8aa3b, v38
	v_exp_f32_e32 v30, v29
	v_mul_f32_e32 v29, 0xbfb8aa3b, v39
	v_exp_f32_e32 v31, v29
	s_nop 0
	v_pk_add_f32 v[30:31], v[30:31], 1.0 op_sel_hi:[1,0]
	s_nop 0
	v_div_scale_f32 v29, s[2:3], v31, v31, v39
	v_rcp_f32_e32 v34, v29
	s_nop 0
	v_fma_f32 v35, -v29, v34, 1.0
	v_fmac_f32_e32 v34, v35, v34
	v_div_scale_f32 v35, vcc, v39, v31, v39
	v_mul_f32_e32 v36, v35, v34
	v_fma_f32 v37, -v29, v36, v35
	v_fmac_f32_e32 v36, v37, v34
	v_fma_f32 v29, -v29, v36, v35
	v_div_fmas_f32 v29, v29, v34, v36
	v_div_fixup_f32 v31, v29, v31, v39
	v_div_scale_f32 v29, s[2:3], v30, v30, v38
	v_rcp_f32_e32 v34, v29
	s_nop 0
	v_fma_f32 v35, -v29, v34, 1.0
	v_fmac_f32_e32 v34, v35, v34
	v_div_scale_f32 v35, vcc, v38, v30, v38
	v_mul_f32_e32 v36, v35, v34
	v_fma_f32 v37, -v29, v36, v35
	v_fmac_f32_e32 v36, v37, v34
	v_fma_f32 v29, -v29, v36, v35
	v_div_fmas_f32 v29, v29, v34, v36
	v_div_fixup_f32 v30, v29, v30, v38
	v_pk_mul_f32 v[30:31], v[30:31], v[32:33]
	s_waitcnt vmcnt(2)
	v_lshlrev_b32_e32 v32, 16, v23
	v_cvt_pk_bf16_f32 v29, v30, v31
	v_lshl_add_u64 v[30:31], s[4:5], 0, v[6:7]
	global_store_dwordx2 v[30:31], v[28:29], off
	v_lshlrev_b32_e32 v28, 16, v25
	v_and_b32_e32 v29, 0xffff0000, v25
	v_lshlrev_b32_e32 v30, 16, v27
	v_and_b32_e32 v31, 0xffff0000, v27
	v_pk_add_f32 v[28:29], v[28:29], v[30:31]
	v_lshlrev_b32_e32 v30, 16, v24
	v_and_b32_e32 v31, 0xffff0000, v24
	v_lshlrev_b32_e32 v24, 16, v26
	v_and_b32_e32 v25, 0xffff0000, v26
	v_pk_add_f32 v[24:25], v[30:31], v[24:25]
	v_mov_b32_e32 v31, v29
	v_mov_b32_e32 v30, v25
	v_mov_b32_e32 v26, v24
	v_mov_b32_e32 v27, v28
	v_pk_mul_f32 v[30:31], v[30:31], v[30:31]
	v_and_b32_e32 v33, 0xffff0000, v23
	v_pk_fma_f32 v[26:27], v[26:27], v[26:27], v[30:31]
	v_lshlrev_b32_e32 v30, 16, v22
	v_add_f32_e32 v26, v26, v27
	v_and_b32_e32 v31, 0xffff0000, v22
	v_mul_f32_e32 v22, 0xbfb8aa3b, v30
	v_mul_f32_e32 v23, 0xbfb8aa3b, v31
	v_exp_f32_e32 v22, v22
	v_exp_f32_e32 v23, v23
	v_add_f32_dpp v26, v26, v26 quad_perm:[1,0,3,2] row_mask:0xf bank_mask:0xf
	v_pk_add_f32 v[22:23], v[22:23], 1.0 op_sel_hi:[1,0]
	s_nop 0
	v_div_scale_f32 v34, s[2:3], v23, v23, v31
	v_rcp_f32_e32 v35, v34
	v_add_f32_dpp v26, v26, v26 quad_perm:[2,3,0,1] row_mask:0xf bank_mask:0xf
	v_fma_f32 v36, -v34, v35, 1.0
	v_fmac_f32_e32 v35, v36, v35
	v_div_scale_f32 v36, vcc, v31, v23, v31
	v_mul_f32_e32 v37, v36, v35
	v_fma_f32 v38, -v34, v37, v36
	v_fmac_f32_e32 v37, v38, v35
	v_add_f32_dpp v26, v26, v26 row_half_mirror row_mask:0xf bank_mask:0xf
	v_fma_f32 v34, -v34, v37, v36
	v_div_fmas_f32 v34, v34, v35, v37
	v_div_fixup_f32 v23, v34, v23, v31
	v_div_scale_f32 v31, s[2:3], v22, v22, v30
	v_rcp_f32_e32 v34, v31
	v_add_f32_dpp v26, v26, v26 row_mirror row_mask:0xf bank_mask:0xf
	ds_bpermute_b32 v27, v48, v26
	v_fma_f32 v35, -v31, v34, 1.0
	v_fmac_f32_e32 v34, v35, v34
	v_div_scale_f32 v35, vcc, v30, v22, v30
	v_mul_f32_e32 v36, v35, v34
	v_fma_f32 v37, -v31, v36, v35
	v_fmac_f32_e32 v36, v37, v34
	s_waitcnt lgkmcnt(0)
	v_add_f32_e32 v26, v26, v27
	v_fma_f32 v31, -v31, v36, v35
	v_fmamk_f32 v26, v26, 0x3c000000, v182
	v_div_fmas_f32 v31, v31, v34, v36
	v_cmp_gt_f32_e32 vcc, s74, v26
	v_mul_f32_e32 v27, 0x4f800000, v26
	v_div_fixup_f32 v22, v31, v22, v30
	v_cndmask_b32_e32 v26, v26, v27, vcc
	v_sqrt_f32_e32 v27, v26
	s_nop 0
	v_add_u32_e32 v30, -1, v27
	v_fma_f32 v31, -v30, v27, v26
	v_cmp_ge_f32_e64 s[2:3], 0, v31
	v_add_u32_e32 v31, 1, v27
	s_nop 0
	v_cndmask_b32_e64 v30, v27, v30, s[2:3]
	v_fma_f32 v27, -v31, v27, v26
	v_cmp_lt_f32_e64 s[2:3], 0, v27
	s_nop 1
	v_cndmask_b32_e64 v27, v30, v31, s[2:3]
	v_mul_f32_e32 v30, 0x37800000, v27
	v_cndmask_b32_e32 v27, v27, v30, vcc
	v_cmp_class_f32_e32 vcc, v26, v183
	s_nop 1
	v_cndmask_b32_e32 v26, v27, v26, vcc
	v_div_scale_f32 v27, s[2:3], v26, v26, 1.0
	v_rcp_f32_e32 v30, v27
	s_nop 0
	v_fma_f32 v31, -v27, v30, 1.0
	v_fmac_f32_e32 v30, v31, v30
	v_div_scale_f32 v31, vcc, 1.0, v26, 1.0
	v_mul_f32_e32 v34, v31, v30
	v_fma_f32 v35, -v27, v34, v31
	v_fmac_f32_e32 v34, v35, v30
	v_fma_f32 v27, -v27, v34, v31
	v_div_fmas_f32 v27, v27, v30, v34
	v_div_fixup_f32 v26, v27, v26, 1.0
	v_pk_mul_f32 v[24:25], v[24:25], v[26:27] op_sel_hi:[1,0]
	v_pk_mul_f32 v[26:27], v[28:29], v[26:27] op_sel_hi:[1,0]
	v_pk_mul_f32 v[24:25], v[0:1], v[24:25]
	v_pk_mul_f32 v[26:27], v[2:3], v[26:27]
	v_pk_mul_f32 v[22:23], v[22:23], v[24:25]
	s_nop 0
	v_cvt_pk_bf16_f32 v22, v22, v23
	v_mul_f32_e32 v23, 0xbfb8aa3b, v32
	v_exp_f32_e32 v24, v23
	v_mul_f32_e32 v23, 0xbfb8aa3b, v33
	v_exp_f32_e32 v25, v23
	s_nop 0
	v_pk_add_f32 v[24:25], v[24:25], 1.0 op_sel_hi:[1,0]
	s_nop 0
	v_div_scale_f32 v23, s[2:3], v25, v25, v33
	v_rcp_f32_e32 v28, v23
	s_nop 0
	v_fma_f32 v29, -v23, v28, 1.0
	v_fmac_f32_e32 v28, v29, v28
	v_div_scale_f32 v29, vcc, v33, v25, v33
	v_mul_f32_e32 v30, v29, v28
	v_fma_f32 v31, -v23, v30, v29
	v_fmac_f32_e32 v30, v31, v28
	v_fma_f32 v23, -v23, v30, v29
	v_div_fmas_f32 v23, v23, v28, v30
	v_div_fixup_f32 v25, v23, v25, v33
	v_div_scale_f32 v23, s[2:3], v24, v24, v32
	v_rcp_f32_e32 v28, v23
	s_nop 0
	v_fma_f32 v29, -v23, v28, 1.0
	v_fmac_f32_e32 v28, v29, v28
	v_div_scale_f32 v29, vcc, v32, v24, v32
	v_mul_f32_e32 v30, v29, v28
	v_fma_f32 v31, -v23, v30, v29
	v_fmac_f32_e32 v30, v31, v28
	v_fma_f32 v23, -v23, v30, v29
	v_div_fmas_f32 v23, v23, v28, v30
	v_div_fixup_f32 v24, v23, v24, v32
	v_pk_mul_f32 v[24:25], v[24:25], v[26:27]
	s_nop 0
	v_cvt_pk_bf16_f32 v23, v24, v25
	v_lshl_add_u64 v[24:25], s[4:5], 0, v[4:5]
	global_store_dwordx2 v[24:25], v[22:23], off
	s_branch .LBB0_741
